# v17 + mlp-up epilogue: canonicalising v_max(x,x) merged into the ReLU v_max(0,x) (112 VALU fewer per tile per wave)
# baseline (speedup 1.0000x reference)
.LBB0_108:
	v_mov_b32_e32 v142, v144
	v_mov_b32_e32 v143, v145
	s_lshl_b32 s4, s22, 8
	s_add_i32 s4, s4, s40
	v_add_u32_e32 v142, s4, v142
	s_lshl_b32 s4, s47, 8
	s_or_b32 s4, s4, s41
	v_lshl_add_u32 v148, v143, 3, s4
	v_ashrrev_i32_e32 v143, 31, v142
	v_lshlrev_b64 v[142:143], 13, v[142:143]
	v_max_f32_e32 v124, 0, v124
	v_max_f32_e32 v125, 0, v125
	v_ashrrev_i32_e32 v149, 31, v148
	v_lshl_add_u64 v[142:143], s[10:11], 0, v[142:143]
	v_lshl_add_u64 v[142:143], v[148:149], 1, v[142:143]
	v_pk_mul_f32 v[148:149], v[124:125], v[124:125]
	v_max_f32_e32 v125, v126, v126
	v_max_f32_e32 v128, 0, v128
	v_max_f32_e32 v129, 0, v129
	v_max_f32_e32 v124, 0, v130
	v_max_f32_e32 v126, 0, v125
	v_max_f32_e32 v125, 0, v131
	v_max_f32_e32 v127, 0, v127
	v_pk_mul_f32 v[128:129], v[128:129], v[128:129]
	v_pk_mul_f32 v[130:131], v[124:125], v[124:125]
	v_pk_mul_f32 v[150:151], v[126:127], v[126:127]
	v_max_f32_e32 v116, 0, v116
	v_max_f32_e32 v117, 0, v117
	v_cvt_pk_bf16_f32 v124, v128, v129
	v_cvt_pk_bf16_f32 v125, v130, v131
	v_cvt_pk_bf16_f32 v126, v148, v149
	v_cvt_pk_bf16_f32 v127, v150, v151
	global_store_dwordx4 v[142:143], v[124:127], off
	v_max_f32_e32 v120, 0, v120
	v_max_f32_e32 v121, 0, v121
	v_pk_mul_f32 v[124:125], v[116:117], v[116:117]
	v_max_f32_e32 v117, v118, v118
	v_max_f32_e32 v116, 0, v122
	v_max_f32_e32 v118, 0, v117
	v_max_f32_e32 v117, 0, v123
	v_max_f32_e32 v119, 0, v119
	v_pk_mul_f32 v[120:121], v[120:121], v[120:121]
	v_pk_mul_f32 v[122:123], v[116:117], v[116:117]
	v_pk_mul_f32 v[126:127], v[118:119], v[118:119]
	v_max_f32_e32 v108, 0, v108
	v_max_f32_e32 v109, 0, v109
	v_cvt_pk_bf16_f32 v116, v120, v121
	v_cvt_pk_bf16_f32 v117, v122, v123
	v_cvt_pk_bf16_f32 v118, v124, v125
	v_cvt_pk_bf16_f32 v119, v126, v127
	global_store_dwordx4 v[142:143], v[116:119], off offset:256
	v_max_f32_e32 v112, 0, v112
	v_max_f32_e32 v113, 0, v113
	v_pk_mul_f32 v[118:119], v[108:109], v[108:109]
	v_max_f32_e32 v109, v110, v110
	s_mov_b64 s[4:5], 0x20000
	v_max_f32_e32 v108, 0, v114
	v_max_f32_e32 v110, 0, v109
	v_max_f32_e32 v109, 0, v115
	v_max_f32_e32 v111, 0, v111
	v_lshl_add_u64 v[116:117], v[142:143], 0, s[4:5]
	v_pk_mul_f32 v[112:113], v[112:113], v[112:113]
	s_mov_b32 s4, 0x20000
	v_pk_mul_f32 v[114:115], v[108:109], v[108:109]
	v_pk_mul_f32 v[120:121], v[110:111], v[110:111]
	v_cvt_pk_bf16_f32 v108, v112, v113
	v_add_co_u32_e32 v112, vcc, s4, v142
	v_max_f32_e32 v100, 0, v100
	v_max_f32_e32 v101, 0, v101
	v_cvt_pk_bf16_f32 v109, v114, v115
	v_cvt_pk_bf16_f32 v110, v118, v119
	v_cvt_pk_bf16_f32 v111, v120, v121
	v_addc_co_u32_e32 v113, vcc, 0, v143, vcc
	global_store_dwordx4 v[112:113], v[108:111], off
	v_max_f32_e32 v104, 0, v104
	v_max_f32_e32 v105, 0, v105
	v_pk_mul_f32 v[108:109], v[100:101], v[100:101]
	v_max_f32_e32 v101, v102, v102
	v_max_f32_e32 v100, 0, v106
	v_max_f32_e32 v102, 0, v101
	v_max_f32_e32 v101, 0, v107
	v_max_f32_e32 v103, 0, v103
	v_pk_mul_f32 v[104:105], v[104:105], v[104:105]
	v_pk_mul_f32 v[106:107], v[100:101], v[100:101]
	v_pk_mul_f32 v[110:111], v[102:103], v[102:103]
	v_max_f32_e32 v92, 0, v92
	v_max_f32_e32 v93, 0, v93
	v_cvt_pk_bf16_f32 v100, v104, v105
	v_cvt_pk_bf16_f32 v101, v106, v107
	v_cvt_pk_bf16_f32 v102, v108, v109
	v_cvt_pk_bf16_f32 v103, v110, v111
	global_store_dwordx4 v[116:117], v[100:103], off offset:256
	v_max_f32_e32 v96, 0, v96
	v_max_f32_e32 v97, 0, v97
	v_pk_mul_f32 v[102:103], v[92:93], v[92:93]
	v_max_f32_e32 v93, v94, v94
	s_mov_b64 s[4:5], 0x40000
	v_max_f32_e32 v92, 0, v98
	v_max_f32_e32 v94, 0, v93
	v_max_f32_e32 v93, 0, v99
	v_max_f32_e32 v95, 0, v95
	v_lshl_add_u64 v[100:101], v[142:143], 0, s[4:5]
	v_pk_mul_f32 v[96:97], v[96:97], v[96:97]
	s_mov_b32 s4, 0x40000
	v_pk_mul_f32 v[98:99], v[92:93], v[92:93]
	v_pk_mul_f32 v[104:105], v[94:95], v[94:95]
	v_cvt_pk_bf16_f32 v92, v96, v97
	v_add_co_u32_e32 v96, vcc, s4, v142
	v_max_f32_e32 v84, 0, v84
	v_max_f32_e32 v85, 0, v85
	v_cvt_pk_bf16_f32 v93, v98, v99
	v_cvt_pk_bf16_f32 v94, v102, v103
	v_cvt_pk_bf16_f32 v95, v104, v105
	v_addc_co_u32_e32 v97, vcc, 0, v143, vcc
	global_store_dwordx4 v[96:97], v[92:95], off
	v_max_f32_e32 v88, 0, v88
	v_max_f32_e32 v89, 0, v89
	v_pk_mul_f32 v[92:93], v[84:85], v[84:85]
	v_max_f32_e32 v85, v86, v86
	v_max_f32_e32 v84, 0, v90
	v_max_f32_e32 v86, 0, v85
	v_max_f32_e32 v85, 0, v91
	v_max_f32_e32 v87, 0, v87
	v_pk_mul_f32 v[88:89], v[88:89], v[88:89]
	v_pk_mul_f32 v[90:91], v[84:85], v[84:85]
	v_pk_mul_f32 v[94:95], v[86:87], v[86:87]
	v_max_f32_e32 v76, 0, v76
	v_max_f32_e32 v77, 0, v77
	v_cvt_pk_bf16_f32 v84, v88, v89
	v_cvt_pk_bf16_f32 v85, v90, v91
	v_cvt_pk_bf16_f32 v86, v92, v93
	v_cvt_pk_bf16_f32 v87, v94, v95
	global_store_dwordx4 v[100:101], v[84:87], off offset:256
	v_max_f32_e32 v80, 0, v80
	v_max_f32_e32 v81, 0, v81
	v_pk_mul_f32 v[86:87], v[76:77], v[76:77]
	v_max_f32_e32 v77, v78, v78
	s_mov_b64 s[4:5], 0x60000
	v_max_f32_e32 v76, 0, v82
	v_max_f32_e32 v78, 0, v77
	v_max_f32_e32 v77, 0, v83
	v_max_f32_e32 v79, 0, v79
	v_lshl_add_u64 v[84:85], v[142:143], 0, s[4:5]
	v_pk_mul_f32 v[80:81], v[80:81], v[80:81]
	s_mov_b32 s4, 0x60000
	v_pk_mul_f32 v[82:83], v[76:77], v[76:77]
	v_pk_mul_f32 v[88:89], v[78:79], v[78:79]
	v_cvt_pk_bf16_f32 v76, v80, v81
	v_add_co_u32_e32 v80, vcc, s4, v142
	v_max_f32_e32 v68, 0, v68
	v_max_f32_e32 v69, 0, v69
	v_cvt_pk_bf16_f32 v77, v82, v83
	v_cvt_pk_bf16_f32 v78, v86, v87
	v_cvt_pk_bf16_f32 v79, v88, v89
	v_addc_co_u32_e32 v81, vcc, 0, v143, vcc
	global_store_dwordx4 v[80:81], v[76:79], off
	v_max_f32_e32 v72, 0, v72
	v_max_f32_e32 v73, 0, v73
	v_pk_mul_f32 v[76:77], v[68:69], v[68:69]
	v_max_f32_e32 v69, v70, v70
	v_max_f32_e32 v68, 0, v74
	v_max_f32_e32 v70, 0, v69
	v_max_f32_e32 v69, 0, v75
	v_max_f32_e32 v71, 0, v71
	v_pk_mul_f32 v[72:73], v[72:73], v[72:73]
	v_pk_mul_f32 v[74:75], v[68:69], v[68:69]
	v_pk_mul_f32 v[78:79], v[70:71], v[70:71]
	v_max_f32_e32 v60, 0, v60
	v_max_f32_e32 v61, 0, v61
	v_cvt_pk_bf16_f32 v68, v72, v73
	v_cvt_pk_bf16_f32 v69, v74, v75
	v_cvt_pk_bf16_f32 v70, v76, v77
	v_cvt_pk_bf16_f32 v71, v78, v79
	global_store_dwordx4 v[84:85], v[68:71], off offset:256
	v_max_f32_e32 v64, 0, v64
	v_max_f32_e32 v65, 0, v65
	v_pk_mul_f32 v[70:71], v[60:61], v[60:61]
	v_max_f32_e32 v61, v62, v62
	s_mov_b64 s[4:5], 0x100000
	v_max_f32_e32 v60, 0, v66
	v_max_f32_e32 v62, 0, v61
	v_max_f32_e32 v61, 0, v67
	v_max_f32_e32 v63, 0, v63
	v_lshl_add_u64 v[68:69], v[142:143], 0, s[4:5]
	v_pk_mul_f32 v[64:65], v[64:65], v[64:65]
	s_mov_b32 s4, 0x100000
	v_pk_mul_f32 v[66:67], v[60:61], v[60:61]
	v_pk_mul_f32 v[72:73], v[62:63], v[62:63]
	v_cvt_pk_bf16_f32 v60, v64, v65
	v_add_co_u32_e32 v64, vcc, s4, v142
	v_max_f32_e32 v52, 0, v52
	v_max_f32_e32 v53, 0, v53
	v_cvt_pk_bf16_f32 v61, v66, v67
	v_cvt_pk_bf16_f32 v62, v70, v71
	v_cvt_pk_bf16_f32 v63, v72, v73
	v_addc_co_u32_e32 v65, vcc, 0, v143, vcc
	global_store_dwordx4 v[64:65], v[60:63], off
	v_max_f32_e32 v56, 0, v56
	v_max_f32_e32 v57, 0, v57
	v_pk_mul_f32 v[60:61], v[52:53], v[52:53]
	v_max_f32_e32 v53, v54, v54
	v_max_f32_e32 v52, 0, v58
	v_max_f32_e32 v54, 0, v53
	v_max_f32_e32 v53, 0, v59
	v_max_f32_e32 v55, 0, v55
	v_pk_mul_f32 v[56:57], v[56:57], v[56:57]
	v_pk_mul_f32 v[58:59], v[52:53], v[52:53]
	v_pk_mul_f32 v[62:63], v[54:55], v[54:55]
	v_max_f32_e32 v44, 0, v44
	v_max_f32_e32 v45, 0, v45
	v_cvt_pk_bf16_f32 v52, v56, v57
	v_cvt_pk_bf16_f32 v53, v58, v59
	v_cvt_pk_bf16_f32 v54, v60, v61
	v_cvt_pk_bf16_f32 v55, v62, v63
	global_store_dwordx4 v[68:69], v[52:55], off offset:256
	v_max_f32_e32 v48, 0, v48
	v_max_f32_e32 v49, 0, v49
	v_pk_mul_f32 v[54:55], v[44:45], v[44:45]
	v_max_f32_e32 v45, v46, v46
	s_mov_b64 s[4:5], 0x120000
	v_max_f32_e32 v44, 0, v50
	v_max_f32_e32 v46, 0, v45
	v_max_f32_e32 v45, 0, v51
	v_max_f32_e32 v47, 0, v47
	v_lshl_add_u64 v[52:53], v[142:143], 0, s[4:5]
	v_pk_mul_f32 v[48:49], v[48:49], v[48:49]
	s_mov_b32 s4, 0x120000
	v_pk_mul_f32 v[50:51], v[44:45], v[44:45]
	v_pk_mul_f32 v[56:57], v[46:47], v[46:47]
	v_cvt_pk_bf16_f32 v44, v48, v49
	v_add_co_u32_e32 v48, vcc, s4, v142
	v_max_f32_e32 v36, 0, v36
	v_max_f32_e32 v37, 0, v37
	v_cvt_pk_bf16_f32 v45, v50, v51
	v_cvt_pk_bf16_f32 v46, v54, v55
	v_cvt_pk_bf16_f32 v47, v56, v57
	v_addc_co_u32_e32 v49, vcc, 0, v143, vcc
	global_store_dwordx4 v[48:49], v[44:47], off
	v_max_f32_e32 v40, 0, v40
	v_max_f32_e32 v41, 0, v41
	v_pk_mul_f32 v[44:45], v[36:37], v[36:37]
	v_max_f32_e32 v37, v38, v38
	v_max_f32_e32 v36, 0, v42
	v_max_f32_e32 v38, 0, v37
	v_max_f32_e32 v37, 0, v43
	v_max_f32_e32 v39, 0, v39
	v_pk_mul_f32 v[40:41], v[40:41], v[40:41]
	v_pk_mul_f32 v[42:43], v[36:37], v[36:37]
	v_pk_mul_f32 v[46:47], v[38:39], v[38:39]
	v_max_f32_e32 v28, 0, v28
	v_max_f32_e32 v29, 0, v29
	v_cvt_pk_bf16_f32 v36, v40, v41
	v_cvt_pk_bf16_f32 v37, v42, v43
	v_cvt_pk_bf16_f32 v38, v44, v45
	v_cvt_pk_bf16_f32 v39, v46, v47
	global_store_dwordx4 v[52:53], v[36:39], off offset:256
	v_max_f32_e32 v32, 0, v32
	v_max_f32_e32 v33, 0, v33
	v_pk_mul_f32 v[38:39], v[28:29], v[28:29]
	v_max_f32_e32 v29, v30, v30
	s_mov_b64 s[4:5], 0x140000
	v_max_f32_e32 v28, 0, v34
	v_max_f32_e32 v30, 0, v29
	v_max_f32_e32 v29, 0, v35
	v_max_f32_e32 v31, 0, v31
	v_lshl_add_u64 v[36:37], v[142:143], 0, s[4:5]
	v_pk_mul_f32 v[32:33], v[32:33], v[32:33]
	s_mov_b32 s4, 0x140000
	v_pk_mul_f32 v[34:35], v[28:29], v[28:29]
	v_pk_mul_f32 v[40:41], v[30:31], v[30:31]
	v_cvt_pk_bf16_f32 v28, v32, v33
	v_add_co_u32_e32 v32, vcc, s4, v142
	v_max_f32_e32 v20, 0, v20
	v_max_f32_e32 v21, 0, v21
	v_cvt_pk_bf16_f32 v29, v34, v35
	v_cvt_pk_bf16_f32 v30, v38, v39
	v_cvt_pk_bf16_f32 v31, v40, v41
	v_addc_co_u32_e32 v33, vcc, 0, v143, vcc
	global_store_dwordx4 v[32:33], v[28:31], off
	v_max_f32_e32 v24, 0, v24
	v_max_f32_e32 v25, 0, v25
	v_pk_mul_f32 v[28:29], v[20:21], v[20:21]
	v_max_f32_e32 v21, v22, v22
	v_max_f32_e32 v20, 0, v26
	v_max_f32_e32 v22, 0, v21
	v_max_f32_e32 v21, 0, v27
	v_max_f32_e32 v23, 0, v23
	v_pk_mul_f32 v[24:25], v[24:25], v[24:25]
	v_pk_mul_f32 v[26:27], v[20:21], v[20:21]
	v_pk_mul_f32 v[30:31], v[22:23], v[22:23]
	v_max_f32_e32 v12, 0, v12
	v_max_f32_e32 v13, 0, v13
	v_cvt_pk_bf16_f32 v20, v24, v25
	v_cvt_pk_bf16_f32 v21, v26, v27
	v_cvt_pk_bf16_f32 v22, v28, v29
	v_cvt_pk_bf16_f32 v23, v30, v31
	global_store_dwordx4 v[36:37], v[20:23], off offset:256
	v_max_f32_e32 v16, 0, v16
	v_max_f32_e32 v17, 0, v17
	v_pk_mul_f32 v[22:23], v[12:13], v[12:13]
	v_max_f32_e32 v13, v14, v14
	s_mov_b64 s[4:5], 0x160000
	v_max_f32_e32 v12, 0, v18
	v_max_f32_e32 v14, 0, v13
	v_max_f32_e32 v13, 0, v19
	v_max_f32_e32 v15, 0, v15
	v_lshl_add_u64 v[20:21], v[142:143], 0, s[4:5]
	v_pk_mul_f32 v[16:17], v[16:17], v[16:17]
	s_mov_b32 s4, 0x160000
	v_pk_mul_f32 v[18:19], v[12:13], v[12:13]
	v_pk_mul_f32 v[24:25], v[14:15], v[14:15]
	v_cvt_pk_bf16_f32 v12, v16, v17
	v_add_co_u32_e32 v16, vcc, s4, v142
	v_max_f32_e32 v4, 0, v4
	v_max_f32_e32 v5, 0, v5
	v_cvt_pk_bf16_f32 v13, v18, v19
	v_cvt_pk_bf16_f32 v14, v22, v23
	v_cvt_pk_bf16_f32 v15, v24, v25
	v_addc_co_u32_e32 v17, vcc, 0, v143, vcc
	global_store_dwordx4 v[16:17], v[12:15], off
	v_max_f32_e32 v8, 0, v8
	v_max_f32_e32 v9, 0, v9
	v_pk_mul_f32 v[12:13], v[4:5], v[4:5]
	v_max_f32_e32 v5, v6, v6
	v_max_f32_e32 v4, 0, v10
	v_max_f32_e32 v6, 0, v5
	v_max_f32_e32 v5, 0, v11
	v_max_f32_e32 v7, 0, v7
	v_pk_mul_f32 v[8:9], v[8:9], v[8:9]
	v_pk_mul_f32 v[10:11], v[4:5], v[4:5]
	v_pk_mul_f32 v[14:15], v[6:7], v[6:7]
	v_cvt_pk_bf16_f32 v4, v8, v9
	v_cvt_pk_bf16_f32 v5, v10, v11
	v_cvt_pk_bf16_f32 v6, v12, v13
	v_cvt_pk_bf16_f32 v7, v14, v15
	s_andn2_b64 vcc, exec, s[6:7]
	s_mov_b64 s[4:5], -1
	s_mov_b32 s54, 0xe10000
	s_movk_i32 s55, 0x1fff
	global_store_dwordx4 v[20:21], v[4:7], off offset:256
	s_cbranch_vccnz .LBB0_101
	s_andn2_b64 vcc, exec, s[8:9]
	s_cbranch_vccnz .LBB0_100
	s_barrier
	s_branch .LBB0_100
